# combined: gather permlane reduction + mask-free chunk body for t>=255 + indexer MFMA/post-processing interleave
# baseline (speedup 1.0000x reference)
.Lg_join:
	v_cvt_pk_bf16_f32 v8, v11, v13
	v_cvt_pk_bf16_f32 v9, v30, v57
	v_add_f32_e32 v30, v42, v57
	v_add_f32_e32 v30, v30, v31
	ds_read_b64_tr_b16 v[10:11], v89
	ds_read_b64_tr_b16 v[12:13], v90
	ds_read_b64_tr_b16 v[38:39], v91
	ds_read_b64_tr_b16 v[40:41], v92
	ds_read_b64_tr_b16 v[34:35], v93
	ds_read_b64_tr_b16 v[36:37], v94
	ds_read_b64_tr_b16 v[170:171], v95
	ds_read_b64_tr_b16 v[172:173], v96
	s_waitcnt lgkmcnt(0)
	s_nop 0
	v_mfma_f32_16x16x32_bf16 v[10:13], v[6:9], v[10:13], v[182:185]
	v_mov_b32_e32 v31, v30
	s_nop 1
	v_permlane16_swap_b32_e32 v30, v31
	v_mfma_f32_16x16x32_bf16 v[38:41], v[6:9], v[38:41], v[174:177]
	v_add_f32_e32 v30, v30, v31
	v_mfma_f32_16x16x32_bf16 v[34:37], v[6:9], v[34:37], v[166:169]
	s_nop 0
	v_mov_b32_e32 v31, v30
	s_nop 1
	v_permlane32_swap_b32_e32 v30, v31
	v_mfma_f32_16x16x32_bf16 v[6:9], v[6:9], v[170:173], v[162:165]
	v_add_f32_e32 v57, v30, v31
	s_nop 0
	v_readlane_b32 s16, v57, 0
	v_readlane_b32 s17, v57, 1
	v_readlane_b32 s18, v57, 2
	v_readlane_b32 s19, v57, 3
	v_mov_b32_e32 v30, s16
	v_mov_b32_e32 v31, s17
	v_mov_b32_e32 v42, s18
	v_mov_b32_e32 v57, s19
	s_and_saveexec_b64 s[14:15], s[6:7]
	s_cbranch_execz .LBB0_977
	s_waitcnt lgkmcnt(0)
	v_div_scale_f32 v59, s[16:17], v57, v57, 1.0
	v_rcp_f32_e32 v155, v59
	s_ashr_i32 s13, s12, 31
	s_lshl_b64 s[10:11], s[10:11], 24
	v_fma_f32 v156, -v59, v155, 1.0
	v_fmac_f32_e32 v155, v156, v155
	v_div_scale_f32 v156, vcc, 1.0, v57, 1.0
	v_mul_f32_e32 v157, v156, v155
	v_fma_f32 v158, -v59, v157, v156
	v_fmac_f32_e32 v157, v158, v155
	v_fma_f32 v59, -v59, v157, v156
	v_div_scale_f32 v156, s[16:17], v42, v42, 1.0
	v_rcp_f32_e32 v158, v156
	v_div_fmas_f32 v59, v59, v155, v157
	v_div_fixup_f32 v57, v59, v57, 1.0
	v_fma_f32 v59, -v156, v158, 1.0
	v_fmac_f32_e32 v158, v59, v158
	v_div_scale_f32 v59, vcc, 1.0, v42, 1.0
	v_mul_f32_e32 v155, v59, v158
	v_fma_f32 v157, -v156, v155, v59
	v_fmac_f32_e32 v155, v157, v158
	v_fma_f32 v59, -v156, v155, v59
	v_div_scale_f32 v156, s[16:17], v31, v31, 1.0
	v_rcp_f32_e32 v157, v156
	v_div_fmas_f32 v59, v59, v158, v155
	v_div_fixup_f32 v42, v59, v42, 1.0
	v_fma_f32 v59, -v156, v157, 1.0
	v_fmac_f32_e32 v157, v59, v157
	v_div_scale_f32 v59, vcc, 1.0, v31, 1.0
	v_mul_f32_e32 v155, v59, v157
	v_fma_f32 v158, -v156, v155, v59
	v_fmac_f32_e32 v155, v158, v157
	v_fma_f32 v59, -v156, v155, v59
	v_div_scale_f32 v156, s[16:17], v30, v30, 1.0
	v_rcp_f32_e32 v158, v156
	v_div_fmas_f32 v59, v59, v157, v155
	v_div_fixup_f32 v155, v59, v31, 1.0
	s_add_u32 s16, s62, s10
	v_fma_f32 v31, -v156, v158, 1.0
	v_fmac_f32_e32 v158, v31, v158
	v_div_scale_f32 v31, vcc, 1.0, v30, 1.0
	v_mul_f32_e32 v59, v31, v158
	v_fma_f32 v157, -v156, v59, v31
	v_fmac_f32_e32 v59, v157, v158
	v_fma_f32 v31, -v156, v59, v31
	v_div_fmas_f32 v31, v31, v158, v59
	s_addc_u32 s17, s63, s11
	s_lshl_b64 s[10:11], s[12:13], 11
	v_div_fixup_f32 v156, v31, v30, 1.0
	s_add_u32 s10, s16, s10
	s_addc_u32 s11, s17, s11
	v_mov_b32_e32 v59, v43
	v_mul_f32_e32 v10, v10, v156
	v_lshl_add_u64 v[30:31], s[10:11], 0, v[58:59]
	v_bfe_u32 v59, v10, 16, 1
	s_lshl_b32 s8, s8, 9
	v_add3_u32 v10, v10, v59, s67
	v_lshl_add_u64 v[30:31], v[30:31], 0, s[8:9]
	global_store_short_d16_hi v[30:31], v10, off
	v_mul_f32_e32 v10, v11, v155
	v_bfe_u32 v11, v10, 16, 1
	v_add3_u32 v10, v10, v11, s67
	global_store_short_d16_hi v[30:31], v10, off offset:128
	v_mul_f32_e32 v10, v12, v42
	v_bfe_u32 v11, v10, 16, 1
	v_add3_u32 v10, v10, v11, s67
	global_store_short_d16_hi v[30:31], v10, off offset:256
	v_mul_f32_e32 v10, v13, v57
	v_bfe_u32 v11, v10, 16, 1
	v_add3_u32 v10, v10, v11, s67
	global_store_short_d16_hi v[30:31], v10, off offset:384
	v_mul_f32_e32 v10, v38, v156
	v_bfe_u32 v11, v10, 16, 1
	v_add3_u32 v10, v10, v11, s67
	global_store_short_d16_hi v[30:31], v10, off offset:32
	v_mul_f32_e32 v10, v39, v155
	v_bfe_u32 v11, v10, 16, 1
	v_add3_u32 v10, v10, v11, s67
	global_store_short_d16_hi v[30:31], v10, off offset:160
	v_mul_f32_e32 v10, v40, v42
	v_bfe_u32 v11, v10, 16, 1
	v_add3_u32 v10, v10, v11, s67
	global_store_short_d16_hi v[30:31], v10, off offset:288
	v_mul_f32_e32 v10, v41, v57
	v_bfe_u32 v11, v10, 16, 1
	v_add3_u32 v10, v10, v11, s67
	global_store_short_d16_hi v[30:31], v10, off offset:416
	v_mul_f32_e32 v10, v34, v156
	v_bfe_u32 v11, v10, 16, 1
	v_add3_u32 v10, v10, v11, s67
	global_store_short_d16_hi v[30:31], v10, off offset:64
	v_mul_f32_e32 v10, v35, v155
	v_bfe_u32 v11, v10, 16, 1
	v_add3_u32 v10, v10, v11, s67
	global_store_short_d16_hi v[30:31], v10, off offset:192
	v_mul_f32_e32 v10, v36, v42
	v_bfe_u32 v11, v10, 16, 1
	v_add3_u32 v10, v10, v11, s67
	global_store_short_d16_hi v[30:31], v10, off offset:320
	v_mul_f32_e32 v10, v37, v57
	v_bfe_u32 v11, v10, 16, 1
	v_add3_u32 v10, v10, v11, s67
	v_mul_f32_e32 v6, v6, v156
	global_store_short_d16_hi v[30:31], v10, off offset:448
	v_bfe_u32 v10, v6, 16, 1
	v_add3_u32 v6, v6, v10, s67
	global_store_short_d16_hi v[30:31], v6, off offset:96
	v_mul_f32_e32 v6, v7, v155
	v_bfe_u32 v7, v6, 16, 1
	v_add3_u32 v6, v6, v7, s67
	global_store_short_d16_hi v[30:31], v6, off offset:224
	v_mul_f32_e32 v6, v8, v42
	v_bfe_u32 v7, v6, 16, 1
	v_add3_u32 v6, v6, v7, s67
	global_store_short_d16_hi v[30:31], v6, off offset:352
	v_mul_f32_e32 v6, v9, v57
	v_bfe_u32 v7, v6, 16, 1
	v_add3_u32 v6, v6, v7, s67
	global_store_short_d16_hi v[30:31], v6, off offset:480
	s_branch .LBB0_977

.LBB0_1032:
	s_or_b64 exec, exec, s[4:5]
	s_add_u32 s12, s28, 0x1c000000
	s_addc_u32 s13, s29, 0
	s_waitcnt lgkmcnt(0)
	v_lshlrev_b32_e32 v1, 1, v212
	s_cmpk_lt_i32 s2, 0x200
	v_readfirstlane_b32 s16, v202
	s_cselect_b64 s[6:7], -1, 0
	s_cmpk_gt_i32 s2, 0x1ff
	v_bitop3_b32 v178, v1, v161, v159 bitop3:0x36
	s_barrier
	s_nop 0
	s_nop 0
	s_nop 0
	s_nop 0
	s_nop 0
	s_nop 0
	s_nop 0
	s_nop 0
	s_nop 0
	s_nop 0
	s_nop 0
	s_nop 0
	s_nop 0
	s_nop 0
	s_nop 0
	s_nop 0
	s_nop 0
	s_nop 0
	s_nop 0
	s_cbranch_scc1 .LBB0_1056
	s_ashr_i32 s37, s2, 31
	s_lshr_b32 s4, s37, 29
	s_add_i32 s8, s2, s4
	s_and_b32 s4, s8, -8
	s_sub_i32 s10, s2, s4
	s_cmp_gt_i32 s10, -1
	s_cbranch_scc0 .LBB0_1035
	s_lshl_b32 s9, s10, 6
	s_cbranch_execz .LBB0_1036
	s_branch .LBB0_1037
